# P1 main K-loop head aligned to 64 bytes (padding sits behind an unconditional branch)
# speedup vs baseline: 1.0033x; 1.0033x over previous
.Lhu_yl:
	ds_read_b128 v[150:153], v248
	ds_read_b128 v[154:157], v248 offset:1024
	ds_read_b128 v[158:161], v248 offset:2048
	ds_read_b128 v[162:165], v248 offset:3072
	ds_read_b128 v[134:137], v249
	ds_read_b128 v[138:141], v249 offset:1024
	ds_read_b128 v[142:145], v249 offset:2048
	ds_read_b128 v[146:149], v249 offset:3072
	ds_read_b128 v[166:169], v250
	ds_read_b128 v[170:173], v250 offset:1024
	ds_read_b128 v[174:177], v250 offset:2048
	ds_read_b128 v[178:181], v250 offset:3072
	ds_read_b128 v[182:185], v250 offset:4096
	ds_read_b128 v[186:189], v250 offset:5120
	ds_read_b128 v[190:193], v250 offset:6144
	ds_read_b128 v[194:197], v250 offset:7168
	s_setprio 1
	s_waitcnt vmcnt(6) lgkmcnt(0)
	s_barrier
	s_add_u32 s88, s2, 0x40000
	s_addc_u32 s89, s3, 0
	s_mov_b32 m0, s73
	s_nop 0
	global_load_lds_dwordx4 v208, s[2:3]
	s_mov_b32 m0, s75
	s_nop 0
	global_load_lds_dwordx4 v212, s[2:3]
	s_mov_b32 m0, s92
	s_nop 0
	global_load_lds_dwordx4 v208, s[88:89]
	s_mov_b32 m0, s93
	s_nop 0
	global_load_lds_dwordx4 v212, s[88:89]
	s_mov_b32 m0, s61
	s_nop 0
	global_load_lds_dwordx4 v206, s[84:85]
	s_mov_b32 m0, s94
	s_nop 0
	global_load_lds_dwordx4 v210, s[84:85]
	s_add_u32 s2, s2, 0x80
	s_addc_u32 s3, s3, 0
	s_add_u32 s84, s84, 0x80
	s_addc_u32 s85, s85, 0
	v_mfma_f32_16x16x32_bf16 v[102:105], v[150:153], v[166:169], v[102:105]
	v_mfma_f32_16x16x32_bf16 v[70:73], v[158:161], v[166:169], v[70:73]
	v_mfma_f32_16x16x32_bf16 v[114:117], v[150:153], v[174:177], v[114:117]
	v_mfma_f32_16x16x32_bf16 v[82:85], v[158:161], v[174:177], v[82:85]
	v_mfma_f32_16x16x32_bf16 v[110:113], v[150:153], v[182:185], v[110:113]
	v_mfma_f32_16x16x32_bf16 v[78:81], v[158:161], v[182:185], v[78:81]
	v_mfma_f32_16x16x32_bf16 v[106:109], v[150:153], v[190:193], v[106:109]
	v_mfma_f32_16x16x32_bf16 v[74:77], v[158:161], v[190:193], v[74:77]
	v_mfma_f32_16x16x32_bf16 v[102:105], v[154:157], v[170:173], v[102:105]
	v_mfma_f32_16x16x32_bf16 v[70:73], v[162:165], v[170:173], v[70:73]
	v_mfma_f32_16x16x32_bf16 v[114:117], v[154:157], v[178:181], v[114:117]
	v_mfma_f32_16x16x32_bf16 v[82:85], v[162:165], v[178:181], v[82:85]
	v_mfma_f32_16x16x32_bf16 v[110:113], v[154:157], v[186:189], v[110:113]
	v_mfma_f32_16x16x32_bf16 v[78:81], v[162:165], v[186:189], v[78:81]
	v_mfma_f32_16x16x32_bf16 v[106:109], v[154:157], v[194:197], v[106:109]
	v_mfma_f32_16x16x32_bf16 v[74:77], v[162:165], v[194:197], v[74:77]
	v_mfma_f32_16x16x32_bf16 v[130:133], v[134:137], v[166:169], v[130:133]
	v_mfma_f32_16x16x32_bf16 v[98:101], v[142:145], v[166:169], v[98:101]
	v_mfma_f32_16x16x32_bf16 v[126:129], v[134:137], v[174:177], v[126:129]
	v_mfma_f32_16x16x32_bf16 v[94:97], v[142:145], v[174:177], v[94:97]
	v_mfma_f32_16x16x32_bf16 v[122:125], v[134:137], v[182:185], v[122:125]
	v_mfma_f32_16x16x32_bf16 v[90:93], v[142:145], v[182:185], v[90:93]
	v_mfma_f32_16x16x32_bf16 v[118:121], v[134:137], v[190:193], v[118:121]
	v_mfma_f32_16x16x32_bf16 v[86:89], v[142:145], v[190:193], v[86:89]
	v_mfma_f32_16x16x32_bf16 v[130:133], v[138:141], v[170:173], v[130:133]
	v_mfma_f32_16x16x32_bf16 v[98:101], v[146:149], v[170:173], v[98:101]
	v_mfma_f32_16x16x32_bf16 v[126:129], v[138:141], v[178:181], v[126:129]
	v_mfma_f32_16x16x32_bf16 v[94:97], v[146:149], v[178:181], v[94:97]
	v_mfma_f32_16x16x32_bf16 v[122:125], v[138:141], v[186:189], v[122:125]
	v_mfma_f32_16x16x32_bf16 v[90:93], v[146:149], v[186:189], v[90:93]
	v_mfma_f32_16x16x32_bf16 v[118:121], v[138:141], v[194:197], v[118:121]
	v_mfma_f32_16x16x32_bf16 v[86:89], v[146:149], v[194:197], v[86:89]
	s_barrier
	s_setprio 0
	ds_read_b128 v[150:153], v220
	ds_read_b128 v[154:157], v220 offset:1024
	ds_read_b128 v[158:161], v220 offset:2048
	ds_read_b128 v[162:165], v220 offset:3072
	ds_read_b128 v[134:137], v221
	ds_read_b128 v[138:141], v221 offset:1024
	ds_read_b128 v[142:145], v221 offset:2048
	ds_read_b128 v[146:149], v221 offset:3072
	ds_read_b128 v[166:169], v250 offset:32768
	ds_read_b128 v[170:173], v250 offset:33792
	ds_read_b128 v[174:177], v250 offset:34816
	ds_read_b128 v[178:181], v250 offset:35840
	ds_read_b128 v[182:185], v250 offset:36864
	ds_read_b128 v[186:189], v250 offset:37888
	ds_read_b128 v[190:193], v250 offset:38912
	ds_read_b128 v[194:197], v250 offset:39936
	s_setprio 1
	s_waitcnt vmcnt(6) lgkmcnt(0)
	s_barrier
	s_add_u32 s88, s2, 0x40000
	s_addc_u32 s89, s3, 0
	s_mov_b32 m0, s54
	s_nop 0
	global_load_lds_dwordx4 v208, s[2:3]
	s_mov_b32 m0, s55
	s_nop 0
	global_load_lds_dwordx4 v212, s[2:3]
	s_mov_b32 m0, s59
	s_nop 0
	global_load_lds_dwordx4 v208, s[88:89]
	s_mov_b32 m0, s24
	s_nop 0
	global_load_lds_dwordx4 v212, s[88:89]
	s_mov_b32 m0, s57
	s_nop 0
	global_load_lds_dwordx4 v206, s[84:85]
	s_mov_b32 m0, s58
	s_nop 0
	global_load_lds_dwordx4 v210, s[84:85]
	s_add_u32 s2, s2, 0x80
	s_addc_u32 s3, s3, 0
	s_add_u32 s84, s84, 0x80
	s_addc_u32 s85, s85, 0
	v_mfma_f32_16x16x32_bf16 v[102:105], v[150:153], v[166:169], v[102:105]
	v_mfma_f32_16x16x32_bf16 v[70:73], v[158:161], v[166:169], v[70:73]
	v_mfma_f32_16x16x32_bf16 v[114:117], v[150:153], v[174:177], v[114:117]
	v_mfma_f32_16x16x32_bf16 v[82:85], v[158:161], v[174:177], v[82:85]
	v_mfma_f32_16x16x32_bf16 v[110:113], v[150:153], v[182:185], v[110:113]
	v_mfma_f32_16x16x32_bf16 v[78:81], v[158:161], v[182:185], v[78:81]
	v_mfma_f32_16x16x32_bf16 v[106:109], v[150:153], v[190:193], v[106:109]
	v_mfma_f32_16x16x32_bf16 v[74:77], v[158:161], v[190:193], v[74:77]
	v_mfma_f32_16x16x32_bf16 v[102:105], v[154:157], v[170:173], v[102:105]
	v_mfma_f32_16x16x32_bf16 v[70:73], v[162:165], v[170:173], v[70:73]
	v_mfma_f32_16x16x32_bf16 v[114:117], v[154:157], v[178:181], v[114:117]
	v_mfma_f32_16x16x32_bf16 v[82:85], v[162:165], v[178:181], v[82:85]
	v_mfma_f32_16x16x32_bf16 v[110:113], v[154:157], v[186:189], v[110:113]
	v_mfma_f32_16x16x32_bf16 v[78:81], v[162:165], v[186:189], v[78:81]
	v_mfma_f32_16x16x32_bf16 v[106:109], v[154:157], v[194:197], v[106:109]
	v_mfma_f32_16x16x32_bf16 v[74:77], v[162:165], v[194:197], v[74:77]
	v_mfma_f32_16x16x32_bf16 v[130:133], v[134:137], v[166:169], v[130:133]
	v_mfma_f32_16x16x32_bf16 v[98:101], v[142:145], v[166:169], v[98:101]
	v_mfma_f32_16x16x32_bf16 v[126:129], v[134:137], v[174:177], v[126:129]
	v_mfma_f32_16x16x32_bf16 v[94:97], v[142:145], v[174:177], v[94:97]
	v_mfma_f32_16x16x32_bf16 v[122:125], v[134:137], v[182:185], v[122:125]
	v_mfma_f32_16x16x32_bf16 v[90:93], v[142:145], v[182:185], v[90:93]
	v_mfma_f32_16x16x32_bf16 v[118:121], v[134:137], v[190:193], v[118:121]
	v_mfma_f32_16x16x32_bf16 v[86:89], v[142:145], v[190:193], v[86:89]
	v_mfma_f32_16x16x32_bf16 v[130:133], v[138:141], v[170:173], v[130:133]
	v_mfma_f32_16x16x32_bf16 v[98:101], v[146:149], v[170:173], v[98:101]
	v_mfma_f32_16x16x32_bf16 v[126:129], v[138:141], v[178:181], v[126:129]
	v_mfma_f32_16x16x32_bf16 v[94:97], v[146:149], v[178:181], v[94:97]
	v_mfma_f32_16x16x32_bf16 v[122:125], v[138:141], v[186:189], v[122:125]
	v_mfma_f32_16x16x32_bf16 v[90:93], v[146:149], v[186:189], v[90:93]
	v_mfma_f32_16x16x32_bf16 v[118:121], v[138:141], v[194:197], v[118:121]
	v_mfma_f32_16x16x32_bf16 v[86:89], v[146:149], v[194:197], v[86:89]
	s_barrier
	s_setprio 0
	ds_read_b128 v[150:153], v222
	ds_read_b128 v[154:157], v222 offset:1024
	ds_read_b128 v[158:161], v222 offset:2048
	ds_read_b128 v[162:165], v222 offset:3072
	ds_read_b128 v[134:137], v223
	ds_read_b128 v[138:141], v223 offset:1024
	ds_read_b128 v[142:145], v223 offset:2048
	ds_read_b128 v[146:149], v223 offset:3072
	ds_read_b128 v[166:169], v250 offset:16384
	ds_read_b128 v[170:173], v250 offset:17408
	ds_read_b128 v[174:177], v250 offset:18432
	ds_read_b128 v[178:181], v250 offset:19456
	ds_read_b128 v[182:185], v250 offset:20480
	ds_read_b128 v[186:189], v250 offset:21504
	ds_read_b128 v[190:193], v250 offset:22528
	ds_read_b128 v[194:197], v250 offset:23552
	s_setprio 1
	s_waitcnt vmcnt(6) lgkmcnt(0)
	s_barrier
	s_add_u32 s88, s2, 0x40000
	s_addc_u32 s89, s3, 0
	s_add_i32 m0, s61, 0xc000
	s_nop 0
	global_load_lds_dwordx4 v208, s[2:3]
	s_add_i32 m0, s61, 0xe000
	s_nop 0
	global_load_lds_dwordx4 v212, s[2:3]
	s_add_i32 m0, s61, 0x20000
	s_nop 0
	global_load_lds_dwordx4 v208, s[88:89]
	s_add_i32 m0, s61, 0x22000
	s_nop 0
	global_load_lds_dwordx4 v212, s[88:89]
	s_mov_b32 m0, s95
	s_nop 0
	global_load_lds_dwordx4 v206, s[84:85]
	s_mov_b32 m0, s96
	s_nop 0
	global_load_lds_dwordx4 v210, s[84:85]
	s_add_u32 s2, s2, 0x80
	s_addc_u32 s3, s3, 0
	s_add_u32 s84, s84, 0x80
	s_addc_u32 s85, s85, 0
	v_mfma_f32_16x16x32_bf16 v[102:105], v[150:153], v[166:169], v[102:105]
	v_mfma_f32_16x16x32_bf16 v[70:73], v[158:161], v[166:169], v[70:73]
	v_mfma_f32_16x16x32_bf16 v[114:117], v[150:153], v[174:177], v[114:117]
	v_mfma_f32_16x16x32_bf16 v[82:85], v[158:161], v[174:177], v[82:85]
	v_mfma_f32_16x16x32_bf16 v[110:113], v[150:153], v[182:185], v[110:113]
	v_mfma_f32_16x16x32_bf16 v[78:81], v[158:161], v[182:185], v[78:81]
	v_mfma_f32_16x16x32_bf16 v[106:109], v[150:153], v[190:193], v[106:109]
	v_mfma_f32_16x16x32_bf16 v[74:77], v[158:161], v[190:193], v[74:77]
	v_mfma_f32_16x16x32_bf16 v[102:105], v[154:157], v[170:173], v[102:105]
	v_mfma_f32_16x16x32_bf16 v[70:73], v[162:165], v[170:173], v[70:73]
	v_mfma_f32_16x16x32_bf16 v[114:117], v[154:157], v[178:181], v[114:117]
	v_mfma_f32_16x16x32_bf16 v[82:85], v[162:165], v[178:181], v[82:85]
	v_mfma_f32_16x16x32_bf16 v[110:113], v[154:157], v[186:189], v[110:113]
	v_mfma_f32_16x16x32_bf16 v[78:81], v[162:165], v[186:189], v[78:81]
	v_mfma_f32_16x16x32_bf16 v[106:109], v[154:157], v[194:197], v[106:109]
	v_mfma_f32_16x16x32_bf16 v[74:77], v[162:165], v[194:197], v[74:77]
	v_mfma_f32_16x16x32_bf16 v[130:133], v[134:137], v[166:169], v[130:133]
	v_mfma_f32_16x16x32_bf16 v[98:101], v[142:145], v[166:169], v[98:101]
	v_mfma_f32_16x16x32_bf16 v[126:129], v[134:137], v[174:177], v[126:129]
	v_mfma_f32_16x16x32_bf16 v[94:97], v[142:145], v[174:177], v[94:97]
	v_mfma_f32_16x16x32_bf16 v[122:125], v[134:137], v[182:185], v[122:125]
	v_mfma_f32_16x16x32_bf16 v[90:93], v[142:145], v[182:185], v[90:93]
	v_mfma_f32_16x16x32_bf16 v[118:121], v[134:137], v[190:193], v[118:121]
	v_mfma_f32_16x16x32_bf16 v[86:89], v[142:145], v[190:193], v[86:89]
	v_mfma_f32_16x16x32_bf16 v[130:133], v[138:141], v[170:173], v[130:133]
	v_mfma_f32_16x16x32_bf16 v[98:101], v[146:149], v[170:173], v[98:101]
	v_mfma_f32_16x16x32_bf16 v[126:129], v[138:141], v[178:181], v[126:129]
	v_mfma_f32_16x16x32_bf16 v[94:97], v[146:149], v[178:181], v[94:97]
	v_mfma_f32_16x16x32_bf16 v[122:125], v[138:141], v[186:189], v[122:125]
	v_mfma_f32_16x16x32_bf16 v[90:93], v[146:149], v[186:189], v[90:93]
	v_mfma_f32_16x16x32_bf16 v[118:121], v[138:141], v[194:197], v[118:121]
	v_mfma_f32_16x16x32_bf16 v[86:89], v[146:149], v[194:197], v[86:89]
	s_barrier
	s_setprio 0
	s_add_i32 s45, s45, 1
	s_cmp_lt_u32 s45, 4
	s_cbranch_scc1 .Lhu_yl
	ds_read_b128 v[150:153], v248
	ds_read_b128 v[154:157], v248 offset:1024
	ds_read_b128 v[158:161], v248 offset:2048
	ds_read_b128 v[162:165], v248 offset:3072
	ds_read_b128 v[134:137], v249
	ds_read_b128 v[138:141], v249 offset:1024
	ds_read_b128 v[142:145], v249 offset:2048
	ds_read_b128 v[146:149], v249 offset:3072
	ds_read_b128 v[166:169], v250
	ds_read_b128 v[170:173], v250 offset:1024
	ds_read_b128 v[174:177], v250 offset:2048
	ds_read_b128 v[178:181], v250 offset:3072
	ds_read_b128 v[182:185], v250 offset:4096
	ds_read_b128 v[186:189], v250 offset:5120
	ds_read_b128 v[190:193], v250 offset:6144
	ds_read_b128 v[194:197], v250 offset:7168
	s_setprio 1
	s_waitcnt vmcnt(6) lgkmcnt(0)
	s_barrier
	s_add_u32 s88, s2, 0x40000
	s_addc_u32 s89, s3, 0
	s_mov_b32 m0, s73
	s_nop 0
	global_load_lds_dwordx4 v208, s[2:3]
	s_mov_b32 m0, s75
	s_nop 0
	global_load_lds_dwordx4 v212, s[2:3]
	s_mov_b32 m0, s92
	s_nop 0
	global_load_lds_dwordx4 v208, s[88:89]
	s_mov_b32 m0, s93
	s_nop 0
	global_load_lds_dwordx4 v212, s[88:89]
	s_mov_b32 m0, s61
	s_nop 0
	global_load_lds_dwordx4 v206, s[84:85]
	s_mov_b32 m0, s94
	s_nop 0
	global_load_lds_dwordx4 v210, s[84:85]
	s_add_u32 s2, s2, 0x80
	s_addc_u32 s3, s3, 0
	s_add_u32 s84, s84, 0x80
	s_addc_u32 s85, s85, 0
	v_mfma_f32_16x16x32_bf16 v[102:105], v[150:153], v[166:169], v[102:105]
	v_mfma_f32_16x16x32_bf16 v[70:73], v[158:161], v[166:169], v[70:73]
	v_mfma_f32_16x16x32_bf16 v[114:117], v[150:153], v[174:177], v[114:117]
	v_mfma_f32_16x16x32_bf16 v[82:85], v[158:161], v[174:177], v[82:85]
	v_mfma_f32_16x16x32_bf16 v[110:113], v[150:153], v[182:185], v[110:113]
	v_mfma_f32_16x16x32_bf16 v[78:81], v[158:161], v[182:185], v[78:81]
	v_mfma_f32_16x16x32_bf16 v[106:109], v[150:153], v[190:193], v[106:109]
	v_mfma_f32_16x16x32_bf16 v[74:77], v[158:161], v[190:193], v[74:77]
	v_mfma_f32_16x16x32_bf16 v[102:105], v[154:157], v[170:173], v[102:105]
	v_mfma_f32_16x16x32_bf16 v[70:73], v[162:165], v[170:173], v[70:73]
	v_mfma_f32_16x16x32_bf16 v[114:117], v[154:157], v[178:181], v[114:117]
	v_mfma_f32_16x16x32_bf16 v[82:85], v[162:165], v[178:181], v[82:85]
	v_mfma_f32_16x16x32_bf16 v[110:113], v[154:157], v[186:189], v[110:113]
	v_mfma_f32_16x16x32_bf16 v[78:81], v[162:165], v[186:189], v[78:81]
	v_mfma_f32_16x16x32_bf16 v[106:109], v[154:157], v[194:197], v[106:109]
	v_mfma_f32_16x16x32_bf16 v[74:77], v[162:165], v[194:197], v[74:77]
	v_mfma_f32_16x16x32_bf16 v[130:133], v[134:137], v[166:169], v[130:133]
	v_mfma_f32_16x16x32_bf16 v[98:101], v[142:145], v[166:169], v[98:101]
	v_mfma_f32_16x16x32_bf16 v[126:129], v[134:137], v[174:177], v[126:129]
	v_mfma_f32_16x16x32_bf16 v[94:97], v[142:145], v[174:177], v[94:97]
	v_mfma_f32_16x16x32_bf16 v[122:125], v[134:137], v[182:185], v[122:125]
	v_mfma_f32_16x16x32_bf16 v[90:93], v[142:145], v[182:185], v[90:93]
	v_mfma_f32_16x16x32_bf16 v[118:121], v[134:137], v[190:193], v[118:121]
	v_mfma_f32_16x16x32_bf16 v[86:89], v[142:145], v[190:193], v[86:89]
	v_mfma_f32_16x16x32_bf16 v[130:133], v[138:141], v[170:173], v[130:133]
	v_mfma_f32_16x16x32_bf16 v[98:101], v[146:149], v[170:173], v[98:101]
	v_mfma_f32_16x16x32_bf16 v[126:129], v[138:141], v[178:181], v[126:129]
	v_mfma_f32_16x16x32_bf16 v[94:97], v[146:149], v[178:181], v[94:97]
	v_mfma_f32_16x16x32_bf16 v[122:125], v[138:141], v[186:189], v[122:125]
	v_mfma_f32_16x16x32_bf16 v[90:93], v[146:149], v[186:189], v[90:93]
	v_mfma_f32_16x16x32_bf16 v[118:121], v[138:141], v[194:197], v[118:121]
	v_mfma_f32_16x16x32_bf16 v[86:89], v[146:149], v[194:197], v[86:89]
	s_barrier
	s_setprio 0
	ds_read_b128 v[150:153], v220
	ds_read_b128 v[154:157], v220 offset:1024
	ds_read_b128 v[158:161], v220 offset:2048
	ds_read_b128 v[162:165], v220 offset:3072
	ds_read_b128 v[134:137], v221
	ds_read_b128 v[138:141], v221 offset:1024
	ds_read_b128 v[142:145], v221 offset:2048
	ds_read_b128 v[146:149], v221 offset:3072
	ds_read_b128 v[166:169], v250 offset:32768
	ds_read_b128 v[170:173], v250 offset:33792
	ds_read_b128 v[174:177], v250 offset:34816
	ds_read_b128 v[178:181], v250 offset:35840
	ds_read_b128 v[182:185], v250 offset:36864
	ds_read_b128 v[186:189], v250 offset:37888
	ds_read_b128 v[190:193], v250 offset:38912
	ds_read_b128 v[194:197], v250 offset:39936
	s_setprio 1
	s_waitcnt vmcnt(6) lgkmcnt(0)
	s_barrier
	v_mfma_f32_16x16x32_bf16 v[102:105], v[150:153], v[166:169], v[102:105]
	v_mfma_f32_16x16x32_bf16 v[70:73], v[158:161], v[166:169], v[70:73]
	v_mfma_f32_16x16x32_bf16 v[114:117], v[150:153], v[174:177], v[114:117]
	v_mfma_f32_16x16x32_bf16 v[82:85], v[158:161], v[174:177], v[82:85]
	v_mfma_f32_16x16x32_bf16 v[110:113], v[150:153], v[182:185], v[110:113]
	v_mfma_f32_16x16x32_bf16 v[78:81], v[158:161], v[182:185], v[78:81]
	v_mfma_f32_16x16x32_bf16 v[106:109], v[150:153], v[190:193], v[106:109]
	v_mfma_f32_16x16x32_bf16 v[74:77], v[158:161], v[190:193], v[74:77]
	v_mfma_f32_16x16x32_bf16 v[102:105], v[154:157], v[170:173], v[102:105]
	v_mfma_f32_16x16x32_bf16 v[70:73], v[162:165], v[170:173], v[70:73]
	v_mfma_f32_16x16x32_bf16 v[114:117], v[154:157], v[178:181], v[114:117]
	v_mfma_f32_16x16x32_bf16 v[82:85], v[162:165], v[178:181], v[82:85]
	v_mfma_f32_16x16x32_bf16 v[110:113], v[154:157], v[186:189], v[110:113]
	v_mfma_f32_16x16x32_bf16 v[78:81], v[162:165], v[186:189], v[78:81]
	v_mfma_f32_16x16x32_bf16 v[106:109], v[154:157], v[194:197], v[106:109]
	v_mfma_f32_16x16x32_bf16 v[74:77], v[162:165], v[194:197], v[74:77]
	v_mfma_f32_16x16x32_bf16 v[130:133], v[134:137], v[166:169], v[130:133]
	v_mfma_f32_16x16x32_bf16 v[98:101], v[142:145], v[166:169], v[98:101]
	v_mfma_f32_16x16x32_bf16 v[126:129], v[134:137], v[174:177], v[126:129]
	v_mfma_f32_16x16x32_bf16 v[94:97], v[142:145], v[174:177], v[94:97]
	v_mfma_f32_16x16x32_bf16 v[122:125], v[134:137], v[182:185], v[122:125]
	v_mfma_f32_16x16x32_bf16 v[90:93], v[142:145], v[182:185], v[90:93]
	v_mfma_f32_16x16x32_bf16 v[118:121], v[134:137], v[190:193], v[118:121]
	v_mfma_f32_16x16x32_bf16 v[86:89], v[142:145], v[190:193], v[86:89]
	v_mfma_f32_16x16x32_bf16 v[130:133], v[138:141], v[170:173], v[130:133]
	v_mfma_f32_16x16x32_bf16 v[98:101], v[146:149], v[170:173], v[98:101]
	v_mfma_f32_16x16x32_bf16 v[126:129], v[138:141], v[178:181], v[126:129]
	v_mfma_f32_16x16x32_bf16 v[94:97], v[146:149], v[178:181], v[94:97]
	v_mfma_f32_16x16x32_bf16 v[122:125], v[138:141], v[186:189], v[122:125]
	v_mfma_f32_16x16x32_bf16 v[90:93], v[146:149], v[186:189], v[90:93]
	v_mfma_f32_16x16x32_bf16 v[118:121], v[138:141], v[194:197], v[118:121]
	v_mfma_f32_16x16x32_bf16 v[86:89], v[146:149], v[194:197], v[86:89]
	s_barrier
	s_setprio 0
	ds_read_b128 v[150:153], v222
	ds_read_b128 v[154:157], v222 offset:1024
	ds_read_b128 v[158:161], v222 offset:2048
	ds_read_b128 v[162:165], v222 offset:3072
	ds_read_b128 v[134:137], v223
	ds_read_b128 v[138:141], v223 offset:1024
	ds_read_b128 v[142:145], v223 offset:2048
	ds_read_b128 v[146:149], v223 offset:3072
	ds_read_b128 v[166:169], v250 offset:16384
	ds_read_b128 v[170:173], v250 offset:17408
	ds_read_b128 v[174:177], v250 offset:18432
	ds_read_b128 v[178:181], v250 offset:19456
	ds_read_b128 v[182:185], v250 offset:20480
	ds_read_b128 v[186:189], v250 offset:21504
	ds_read_b128 v[190:193], v250 offset:22528
	ds_read_b128 v[194:197], v250 offset:23552
	s_setprio 1
	s_waitcnt vmcnt(0) lgkmcnt(0)
	s_barrier
	v_mfma_f32_16x16x32_bf16 v[102:105], v[150:153], v[166:169], v[102:105]
	v_mfma_f32_16x16x32_bf16 v[70:73], v[158:161], v[166:169], v[70:73]
	v_mfma_f32_16x16x32_bf16 v[114:117], v[150:153], v[174:177], v[114:117]
	v_mfma_f32_16x16x32_bf16 v[82:85], v[158:161], v[174:177], v[82:85]
	v_mfma_f32_16x16x32_bf16 v[110:113], v[150:153], v[182:185], v[110:113]
	v_mfma_f32_16x16x32_bf16 v[78:81], v[158:161], v[182:185], v[78:81]
	v_mfma_f32_16x16x32_bf16 v[106:109], v[150:153], v[190:193], v[106:109]
	v_mfma_f32_16x16x32_bf16 v[74:77], v[158:161], v[190:193], v[74:77]
	v_mfma_f32_16x16x32_bf16 v[102:105], v[154:157], v[170:173], v[102:105]
	v_mfma_f32_16x16x32_bf16 v[70:73], v[162:165], v[170:173], v[70:73]
	v_mfma_f32_16x16x32_bf16 v[114:117], v[154:157], v[178:181], v[114:117]
	v_mfma_f32_16x16x32_bf16 v[82:85], v[162:165], v[178:181], v[82:85]
	v_mfma_f32_16x16x32_bf16 v[110:113], v[154:157], v[186:189], v[110:113]
	v_mfma_f32_16x16x32_bf16 v[78:81], v[162:165], v[186:189], v[78:81]
	v_mfma_f32_16x16x32_bf16 v[106:109], v[154:157], v[194:197], v[106:109]
	v_mfma_f32_16x16x32_bf16 v[74:77], v[162:165], v[194:197], v[74:77]
	v_mfma_f32_16x16x32_bf16 v[130:133], v[134:137], v[166:169], v[130:133]
	v_mfma_f32_16x16x32_bf16 v[98:101], v[142:145], v[166:169], v[98:101]
	v_mfma_f32_16x16x32_bf16 v[126:129], v[134:137], v[174:177], v[126:129]
	v_mfma_f32_16x16x32_bf16 v[94:97], v[142:145], v[174:177], v[94:97]
	v_mfma_f32_16x16x32_bf16 v[122:125], v[134:137], v[182:185], v[122:125]
	v_mfma_f32_16x16x32_bf16 v[90:93], v[142:145], v[182:185], v[90:93]
	v_mfma_f32_16x16x32_bf16 v[118:121], v[134:137], v[190:193], v[118:121]
	v_mfma_f32_16x16x32_bf16 v[86:89], v[142:145], v[190:193], v[86:89]
	v_mfma_f32_16x16x32_bf16 v[130:133], v[138:141], v[170:173], v[130:133]
	v_mfma_f32_16x16x32_bf16 v[98:101], v[146:149], v[170:173], v[98:101]
	v_mfma_f32_16x16x32_bf16 v[126:129], v[138:141], v[178:181], v[126:129]
	v_mfma_f32_16x16x32_bf16 v[94:97], v[146:149], v[178:181], v[94:97]
	v_mfma_f32_16x16x32_bf16 v[122:125], v[138:141], v[186:189], v[122:125]
	v_mfma_f32_16x16x32_bf16 v[90:93], v[146:149], v[186:189], v[90:93]
	v_mfma_f32_16x16x32_bf16 v[118:121], v[138:141], v[194:197], v[118:121]
	v_mfma_f32_16x16x32_bf16 v[86:89], v[146:149], v[194:197], v[86:89]
	s_barrier
	s_setprio 0
	ds_read_b128 v[150:153], v248
	ds_read_b128 v[154:157], v248 offset:1024
	ds_read_b128 v[158:161], v248 offset:2048
	ds_read_b128 v[162:165], v248 offset:3072
	ds_read_b128 v[134:137], v249
	ds_read_b128 v[138:141], v249 offset:1024
	ds_read_b128 v[142:145], v249 offset:2048
	ds_read_b128 v[146:149], v249 offset:3072
	ds_read_b128 v[166:169], v250
	ds_read_b128 v[170:173], v250 offset:1024
	ds_read_b128 v[174:177], v250 offset:2048
	ds_read_b128 v[178:181], v250 offset:3072
	ds_read_b128 v[182:185], v250 offset:4096
	ds_read_b128 v[186:189], v250 offset:5120
	ds_read_b128 v[190:193], v250 offset:6144
	ds_read_b128 v[194:197], v250 offset:7168
	s_setprio 1
	s_waitcnt vmcnt(0) lgkmcnt(0)
	s_barrier
	v_mfma_f32_16x16x32_bf16 v[102:105], v[150:153], v[166:169], v[102:105]
	v_mfma_f32_16x16x32_bf16 v[70:73], v[158:161], v[166:169], v[70:73]
	v_mfma_f32_16x16x32_bf16 v[114:117], v[150:153], v[174:177], v[114:117]
	v_mfma_f32_16x16x32_bf16 v[82:85], v[158:161], v[174:177], v[82:85]
	v_mfma_f32_16x16x32_bf16 v[110:113], v[150:153], v[182:185], v[110:113]
	v_mfma_f32_16x16x32_bf16 v[78:81], v[158:161], v[182:185], v[78:81]
	v_mfma_f32_16x16x32_bf16 v[106:109], v[150:153], v[190:193], v[106:109]
	v_mfma_f32_16x16x32_bf16 v[74:77], v[158:161], v[190:193], v[74:77]
	v_mfma_f32_16x16x32_bf16 v[102:105], v[154:157], v[170:173], v[102:105]
	v_mfma_f32_16x16x32_bf16 v[70:73], v[162:165], v[170:173], v[70:73]
	v_mfma_f32_16x16x32_bf16 v[114:117], v[154:157], v[178:181], v[114:117]
	v_mfma_f32_16x16x32_bf16 v[82:85], v[162:165], v[178:181], v[82:85]
	v_mfma_f32_16x16x32_bf16 v[110:113], v[154:157], v[186:189], v[110:113]
	v_mfma_f32_16x16x32_bf16 v[78:81], v[162:165], v[186:189], v[78:81]
	v_mfma_f32_16x16x32_bf16 v[106:109], v[154:157], v[194:197], v[106:109]
	v_mfma_f32_16x16x32_bf16 v[74:77], v[162:165], v[194:197], v[74:77]
	v_mfma_f32_16x16x32_bf16 v[130:133], v[134:137], v[166:169], v[130:133]
	v_mfma_f32_16x16x32_bf16 v[98:101], v[142:145], v[166:169], v[98:101]
	v_mfma_f32_16x16x32_bf16 v[126:129], v[134:137], v[174:177], v[126:129]
	v_mfma_f32_16x16x32_bf16 v[94:97], v[142:145], v[174:177], v[94:97]
	v_mfma_f32_16x16x32_bf16 v[122:125], v[134:137], v[182:185], v[122:125]
	v_mfma_f32_16x16x32_bf16 v[90:93], v[142:145], v[182:185], v[90:93]
	v_mfma_f32_16x16x32_bf16 v[118:121], v[134:137], v[190:193], v[118:121]
	v_mfma_f32_16x16x32_bf16 v[86:89], v[142:145], v[190:193], v[86:89]
	v_mfma_f32_16x16x32_bf16 v[130:133], v[138:141], v[170:173], v[130:133]
	v_mfma_f32_16x16x32_bf16 v[98:101], v[146:149], v[170:173], v[98:101]
	v_mfma_f32_16x16x32_bf16 v[126:129], v[138:141], v[178:181], v[126:129]
	v_mfma_f32_16x16x32_bf16 v[94:97], v[146:149], v[178:181], v[94:97]
	v_mfma_f32_16x16x32_bf16 v[122:125], v[138:141], v[186:189], v[122:125]
	v_mfma_f32_16x16x32_bf16 v[90:93], v[146:149], v[186:189], v[90:93]
	v_mfma_f32_16x16x32_bf16 v[118:121], v[138:141], v[194:197], v[118:121]
	v_mfma_f32_16x16x32_bf16 v[86:89], v[146:149], v[194:197], v[86:89]
	s_barrier
	s_setprio 0
	s_mov_b64 s[0:1], -1
	s_branch .LBB0_122
	.p2align 6
